# attention: last four P.V MFMAs of each Y segment issued at the head of the next X segment behind the K fragment reads
# speedup vs baseline: 1.0132x; 1.0031x over previous
.LBB0_622:
	v_add3_u32 v165, s57, v143, v163
	ds_read_b128 v[190:193], v165 offset:18432
	ds_read_b128 v[194:197], v165 offset:18448
	ds_read_b128 v[128:131], v165 offset:23040
	ds_read_b128 v[132:135], v165 offset:23056
	ds_read_b128 v[136:139], v165 offset:27648
	ds_read_b128 v[166:169], v165 offset:27664
	ds_read_b128 v[170:173], v165 offset:32256
	ds_read_b128 v[178:181], v165 offset:32272
	v_exp_f32_e32 v96, v96
	v_exp_f32_e32 v97, v97
	v_exp_f32_e32 v98, v98
	v_exp_f32_e32 v99, v99
	v_exp_f32_e32 v100, v100
	v_add_f32_e32 v198, v97, v96
	v_exp_f32_e32 v101, v101
	v_add_f32_e32 v198, v98, v198
	v_exp_f32_e32 v102, v102
	v_add_f32_e32 v198, v99, v198
	v_exp_f32_e32 v103, v103
	v_add_f32_e32 v198, v100, v198
	v_exp_f32_e32 v104, v104
	v_add_f32_e32 v198, v101, v198
	v_exp_f32_e32 v105, v105
	v_add_f32_e32 v198, v102, v198
	v_exp_f32_e32 v106, v106
	v_add_f32_e32 v198, v103, v198
	v_exp_f32_e32 v107, v107
	v_add_f32_e32 v198, v104, v198
	v_exp_f32_e32 v108, v108
	v_add_f32_e32 v198, v105, v198
	v_exp_f32_e32 v109, v109
	v_add_f32_e32 v198, v106, v198
	v_exp_f32_e32 v110, v110
	v_add_f32_e32 v198, v107, v198
	v_exp_f32_e32 v111, v111
	v_add_f32_e32 v198, v108, v198
	v_add_f32_e32 v198, v109, v198
	v_add_f32_e32 v198, v110, v198
	v_add_f32_e32 v198, v111, v198
	v_add_f32_e32 v157, v157, v198
	v_cvt_pk_bf16_f32 v96, v96, v97
	v_cvt_pk_bf16_f32 v97, v98, v99
	v_cvt_pk_bf16_f32 v98, v100, v101
	v_cvt_pk_bf16_f32 v99, v102, v103
	v_cvt_pk_bf16_f32 v100, v104, v105
	v_cvt_pk_bf16_f32 v101, v106, v107
	v_cvt_pk_bf16_f32 v102, v108, v109
	v_cvt_pk_bf16_f32 v103, v110, v111
	s_waitcnt lgkmcnt(7)
	v_mfma_f32_32x32x16_bf16 v[48:63], v[190:193], v[96:99], v[48:63]
	v_exp_f32_e32 v174, v80
	v_exp_f32_e32 v175, v81
	v_exp_f32_e32 v182, v82
	v_exp_f32_e32 v183, v83
	v_add_f32_e32 v80, v175, v174
	v_add_f32_e32 v80, v182, v80
	s_waitcnt lgkmcnt(5)
	v_mfma_f32_32x32x16_bf16 v[0:15], v[128:131], v[96:99], v[0:15]
	v_add_f32_e32 v80, v183, v80
	v_mfma_f32_32x32x16_bf16 v[48:63], v[194:197], v[100:103], v[48:63]
	v_exp_f32_e32 v128, v84
	v_exp_f32_e32 v129, v85
	v_exp_f32_e32 v130, v86
	v_exp_f32_e32 v131, v87
	v_add_f32_e32 v80, v128, v80
	v_add_f32_e32 v80, v129, v80
	v_add_f32_e32 v80, v130, v80
	s_waitcnt lgkmcnt(4)
	v_mfma_f32_32x32x16_bf16 v[0:15], v[132:135], v[100:103], v[0:15]
	v_add_f32_e32 v184, v131, v80
	ds_read_b128 v[80:83], v165 offset:18496
	ds_read_b128 v[84:87], v165 offset:18512
	ds_read_b128 v[104:107], v165 offset:23104
	ds_read_b128 v[108:111], v165 offset:23120
	s_waitcnt lgkmcnt(7)
	v_mfma_f32_32x32x16_bf16 v[32:47], v[136:139], v[96:99], v[32:47]
	v_exp_f32_e32 v132, v88
	v_exp_f32_e32 v133, v89
	v_exp_f32_e32 v134, v90
	v_exp_f32_e32 v135, v91
	v_add_f32_e32 v88, v132, v184
	v_add_f32_e32 v88, v133, v88
	v_add_f32_e32 v88, v134, v88
	s_waitcnt lgkmcnt(5)
	v_mfma_f32_32x32x16_bf16 v[16:31], v[170:173], v[96:99], v[16:31]
	v_add_f32_e32 v88, v135, v88
	v_exp_f32_e32 v96, v92
	v_mfma_f32_32x32x16_bf16 v[32:47], v[166:169], v[100:103], v[32:47]
	v_exp_f32_e32 v97, v93
	v_exp_f32_e32 v98, v94
	v_exp_f32_e32 v95, v95
	v_add_f32_e32 v88, v96, v88
	v_add_f32_e32 v88, v97, v88
	v_add_f32_e32 v88, v98, v88
	v_add_f32_e32 v88, v95, v88
	s_waitcnt lgkmcnt(4)
	v_mfma_f32_32x32x16_bf16 v[16:31], v[178:181], v[100:103], v[16:31]
	v_add_f32_e32 v157, v157, v88
	v_cvt_pk_bf16_f32 v88, v174, v175
	v_cvt_pk_bf16_f32 v89, v182, v183
	v_cvt_pk_bf16_f32 v90, v128, v129
	v_cvt_pk_bf16_f32 v91, v130, v131
	v_cvt_pk_bf16_f32 v92, v132, v133
	v_cvt_pk_bf16_f32 v93, v134, v135
	v_cvt_pk_bf16_f32 v94, v96, v97
	v_cvt_pk_bf16_f32 v95, v98, v95
	ds_read_b128 v[96:99], v165 offset:27712
	ds_read_b128 v[100:103], v165 offset:27728
	ds_read_b128 v[128:131], v165 offset:32320
	ds_read_b128 v[132:135], v165 offset:32336
	s_waitcnt lgkmcnt(7)
	v_mfma_f32_32x32x16_bf16 v[48:63], v[80:83], v[88:91], v[48:63]
	s_waitcnt lgkmcnt(5)
	v_mfma_f32_32x32x16_bf16 v[0:15], v[104:107], v[88:91], v[0:15]
	s_add_i32 s4, s9, 0x9000
	s_cmp_lg_u32 s9, 0x12000
	s_cselect_b32 s9, s4, 0
	v_mfma_f32_32x32x16_bf16 v[48:63], v[84:87], v[92:95], v[48:63]
	s_waitcnt lgkmcnt(4)
	v_mfma_f32_32x32x16_bf16 v[0:15], v[108:111], v[92:95], v[0:15]
	s_add_i32 s4, s56, 1
	s_cmp_lg_u32 s56, 2
	s_cselect_b32 s56, s4, 0
	s_add_i32 s8, s8, 1
	s_add_i32 s87, s87, 64
	s_cmpk_lg_i32 s87, 0xfc0
	s_waitcnt lgkmcnt(0)
	s_barrier
	s_cbranch_scc0 .Lv1p_flush
	s_add_i32 s57, s9, 0
	s_add_i32 s4, s57, s94
	v_add_u32_e32 v80, s4, v162
	v_add_u32_e32 v84, v80, v146
	ds_read_b128 v[80:83], v84
	ds_read_b128 v[220:223], v84 offset:32
	ds_read_b128 v[136:139], v84 offset:4608
	ds_read_b128 v[224:227], v84 offset:4640
	ds_read_b128 v[166:169], v84 offset:64
	ds_read_b128 v[170:173], v84 offset:96
	ds_read_b128 v[178:181], v84 offset:4672
	ds_read_b128 v[182:185], v84 offset:4704
	v_mfma_f32_32x32x16_bf16 v[32:47], v[96:99], v[88:91], v[32:47]
	v_mfma_f32_32x32x16_bf16 v[16:31], v[128:131], v[88:91], v[16:31]
	v_mfma_f32_32x32x16_bf16 v[32:47], v[100:103], v[92:95], v[32:47]
	v_mfma_f32_32x32x16_bf16 v[16:31], v[132:135], v[92:95], v[16:31]
	s_branch .Lv1p_body
.LBB0_623:
	s_add_i32 s57, s9, 0
	s_add_i32 s4, s57, s94
	v_add_u32_e32 v80, s4, v162
	v_add_u32_e32 v84, v80, v146
	ds_read_b128 v[80:83], v84
	ds_read_b128 v[220:223], v84 offset:32
	ds_read_b128 v[136:139], v84 offset:4608
	ds_read_b128 v[224:227], v84 offset:4640
	ds_read_b128 v[166:169], v84 offset:64
	ds_read_b128 v[170:173], v84 offset:96
	ds_read_b128 v[178:181], v84 offset:4672
	ds_read_b128 v[182:185], v84 offset:4704
.Lv1p_body:
	s_cmp_gt_u32 s8, 61
	s_cselect_b64 s[78:79], -1, 0
	s_and_b64 vcc, exec, s[78:79]
	s_cbranch_vccnz .LBB0_625
	s_mul_i32 s16, s56, 0x9000
	s_add_i32 s17, s16, s35
	s_and_b64 s[80:81], s[54:55], exec
	s_cselect_b32 m0, s17, s82
	s_nop 0
	global_load_lds_dwordx4 v[240:241], off
	s_add_i32 s17, s16, s33
	s_and_b64 s[80:81], s[64:65], exec
	s_cselect_b32 m0, s17, s2
	v_lshl_add_u64 v[240:241], v[240:241], 0, v[200:201]
	global_load_lds_dwordx4 v[242:243], off
	s_add_i32 s17, s16, s93
	s_and_b64 s[80:81], s[42:43], exec
	s_cselect_b32 m0, s17, s92
	v_lshl_add_u64 v[242:243], v[242:243], 0, v[202:203]
	global_load_lds_dwordx4 v[244:245], off
	s_add_i32 s17, s16, s45
	s_and_b64 s[80:81], s[24:25], exec
	s_cselect_b32 m0, s17, s97
	v_lshl_add_u64 v[244:245], v[244:245], 0, v[204:205]
	global_load_lds_dwordx4 v[246:247], off
	s_add_i32 s17, s16, s59
	s_and_b64 s[80:81], s[70:71], exec
	s_cselect_b32 m0, s17, s27
	v_lshl_add_u64 v[246:247], v[246:247], 0, v[206:207]
	global_load_lds_dwordx4 v[248:249], off
	v_lshl_add_u64 v[248:249], v[248:249], 0, v[208:209]

.Lattn_negm_keep_0:
	s_addk_i32 s16, 0xffa1
	s_cmp_lt_u32 s16, 0xfffffea3
	s_nop 0
	s_waitcnt lgkmcnt(7)
	v_mfma_f32_32x32x16_bf16 v[96:111], v[80:83], v[112:115], v[64:79]
	s_waitcnt lgkmcnt(5)
	v_mfma_f32_32x32x16_bf16 v[80:95], v[136:139], v[112:115], v[64:79]
	v_mfma_f32_32x32x16_bf16 v[96:111], v[220:223], v[116:119], v[96:111]
	s_waitcnt lgkmcnt(4)
	v_mfma_f32_32x32x16_bf16 v[80:95], v[224:227], v[116:119], v[80:95]
	s_waitcnt lgkmcnt(3)
	v_mfma_f32_32x32x16_bf16 v[96:111], v[166:169], v[120:123], v[96:111]
	s_waitcnt lgkmcnt(1)
	v_mfma_f32_32x32x16_bf16 v[80:95], v[178:181], v[120:123], v[80:95]
	v_mfma_f32_32x32x16_bf16 v[96:111], v[170:173], v[124:127], v[96:111]
	s_waitcnt lgkmcnt(0)
	v_mfma_f32_32x32x16_bf16 v[80:95], v[182:185], v[124:127], v[80:95]
	s_cbranch_scc1 .LBB0_627
	v_add_u32_e32 v180, s87, v164
	s_mov_b32 s80, 0x20380
	v_lshl_add_u32 v250, v180, 2, s80
	ds_read2_b32 v[128:129], v250 offset0:0 offset1:1
	ds_read2_b32 v[132:133], v250 offset0:2 offset1:3
	ds_read2_b32 v[136:137], v250 offset0:4 offset1:5
	ds_read2_b32 v[166:167], v250 offset0:6 offset1:7
	ds_read2_b32 v[170:171], v250 offset0:8 offset1:9
	ds_read2_b32 v[174:175], v250 offset0:10 offset1:11
	ds_read2_b32 v[180:181], v250 offset0:12 offset1:13
	ds_read2_b32 v[184:185], v250 offset0:14 offset1:15
	ds_read2_b32 v[130:131], v250 offset0:32 offset1:33
	ds_read2_b32 v[134:135], v250 offset0:34 offset1:35
	ds_read2_b32 v[138:139], v250 offset0:36 offset1:37
	ds_read2_b32 v[168:169], v250 offset0:38 offset1:39
	ds_read2_b32 v[172:173], v250 offset0:40 offset1:41
	ds_read2_b32 v[178:179], v250 offset0:42 offset1:43
	ds_read2_b32 v[182:183], v250 offset0:44 offset1:45
	ds_read2_b32 v[186:187], v250 offset0:46 offset1:47
	s_waitcnt lgkmcnt(0)
	v_pk_add_f32 v[110:111], v[110:111], v[184:185]
	v_pk_add_f32 v[108:109], v[108:109], v[180:181]
	v_pk_add_f32 v[106:107], v[106:107], v[174:175]
	v_pk_add_f32 v[104:105], v[104:105], v[170:171]
	v_pk_add_f32 v[102:103], v[102:103], v[166:167]
	v_pk_add_f32 v[100:101], v[100:101], v[136:137]
	v_pk_add_f32 v[98:99], v[98:99], v[132:133]
	v_pk_add_f32 v[96:97], v[96:97], v[128:129]
	v_pk_add_f32 v[94:95], v[94:95], v[186:187]
	v_pk_add_f32 v[92:93], v[92:93], v[182:183]
	v_pk_add_f32 v[90:91], v[90:91], v[178:179]
	v_pk_add_f32 v[88:89], v[88:89], v[172:173]
	v_pk_add_f32 v[86:87], v[86:87], v[168:169]
	v_pk_add_f32 v[84:85], v[84:85], v[138:139]
	v_pk_add_f32 v[82:83], v[82:83], v[134:135]
	v_pk_add_f32 v[80:81], v[80:81], v[130:131]

.Lv1p_flush:
	v_mfma_f32_32x32x16_bf16 v[32:47], v[96:99], v[88:91], v[32:47]
	v_mfma_f32_32x32x16_bf16 v[16:31], v[128:131], v[88:91], v[16:31]
	v_mfma_f32_32x32x16_bf16 v[32:47], v[100:103], v[92:95], v[32:47]
	v_mfma_f32_32x32x16_bf16 v[16:31], v[132:135], v[92:95], v[16:31]

.LBB0_638:
	s_cmpk_eq_i32 s20, 0xfc0
	s_cbranch_scc1 .Lv2p_flush
	s_add_i32 s50, s44, 0
	v_add3_u32 v84, s50, v162, v146
	ds_read_b128 v[80:83], v84
	ds_read_b128 v[128:131], v84 offset:32
	ds_read_b128 v[132:135], v84 offset:4608
	ds_read_b128 v[136:139], v84 offset:4640
	ds_read_b128 v[140:143], v84 offset:64
	ds_read_b128 v[220:223], v84 offset:96
	ds_read_b128 v[224:227], v84 offset:4672
	ds_read_b128 v[228:231], v84 offset:4704
	v_mfma_f32_32x32x16_bf16 v[32:47], v[182:185], v[170:173], v[32:47]
	v_mfma_f32_32x32x16_bf16 v[16:31], v[190:193], v[170:173], v[16:31]
	v_mfma_f32_32x32x16_bf16 v[32:47], v[186:189], v[178:181], v[32:47]
	v_mfma_f32_32x32x16_bf16 v[16:31], v[194:197], v[178:181], v[16:31]
	s_branch .Lv2p_body
.LBB0_639:
	s_add_i32 s50, s44, 0
	v_add3_u32 v84, s50, v162, v146
	ds_read_b128 v[80:83], v84
	ds_read_b128 v[128:131], v84 offset:32
	ds_read_b128 v[132:135], v84 offset:4608
	ds_read_b128 v[136:139], v84 offset:4640
	ds_read_b128 v[140:143], v84 offset:64
	ds_read_b128 v[220:223], v84 offset:96
	ds_read_b128 v[224:227], v84 offset:4672
	ds_read_b128 v[228:231], v84 offset:4704
.Lv2p_body:
	s_add_i32 s51, s27, s20
	s_add_i32 s4, s51, 64
	s_cmpk_lt_i32 s4, 0xff42
	s_cselect_b32 s5, 1, 0
	s_cmpk_gt_i32 s4, 0x9e
	s_cselect_b32 s4, 2, s5
	s_cmp_eq_u32 s4, s32
	s_cbranch_scc1 .Lattn_negm_keep_1
	s_mov_b32 s32, s4
	s_cmp_eq_u32 s4, 1
	s_cselect_b64 vcc, -1, 0
	s_cmp_eq_u32 s4, 2
	s_cselect_b64 s[4:5], -1, 0
	v_cndmask_b32_e64 v84, 0, v160, s[4:5]
	v_cndmask_b32_e32 v252, v84, v159, vcc
	v_sub_f32_e32 v84, v252, v156
	v_mov_b32_e32 v79, v84
	v_mov_b32_e32 v78, v84
	v_mov_b32_e32 v77, v84
	v_mov_b32_e32 v76, v84
	v_mov_b32_e32 v75, v84
	v_mov_b32_e32 v74, v84
	v_mov_b32_e32 v73, v84
	v_mov_b32_e32 v72, v84
	v_mov_b32_e32 v71, v84
	v_mov_b32_e32 v70, v84
	v_mov_b32_e32 v69, v84
	v_mov_b32_e32 v68, v84
	v_mov_b32_e32 v67, v84
	v_mov_b32_e32 v66, v84
	v_mov_b32_e32 v65, v84
	v_mov_b32_e32 v64, v84
.Lattn_negm_keep_1:
	s_addk_i32 s51, 0xffa1
	s_cmp_lt_u32 s51, 0xfffffea3
	s_nop 0
	s_waitcnt lgkmcnt(7)
	v_mfma_f32_32x32x16_bf16 v[96:111], v[80:83], v[112:115], v[64:79]
	s_waitcnt lgkmcnt(5)
	v_mfma_f32_32x32x16_bf16 v[80:95], v[132:135], v[112:115], v[64:79]
	v_mfma_f32_32x32x16_bf16 v[96:111], v[128:131], v[116:119], v[96:111]
	s_waitcnt lgkmcnt(4)
	v_mfma_f32_32x32x16_bf16 v[80:95], v[136:139], v[116:119], v[80:95]
	s_waitcnt lgkmcnt(3)
	v_mfma_f32_32x32x16_bf16 v[96:111], v[140:143], v[120:123], v[96:111]
	s_waitcnt lgkmcnt(1)
	v_mfma_f32_32x32x16_bf16 v[80:95], v[224:227], v[120:123], v[80:95]
	v_mfma_f32_32x32x16_bf16 v[96:111], v[220:223], v[124:127], v[96:111]
	s_waitcnt lgkmcnt(0)
	v_mfma_f32_32x32x16_bf16 v[80:95], v[228:231], v[124:127], v[80:95]
	s_cbranch_scc1 .LBB0_641
	v_add_u32_e32 v178, s20, v166
	s_mov_b32 s51, 0x20380
	v_lshl_add_u32 v250, v178, 2, s51
	ds_read2_b32 v[128:129], v250 offset0:0 offset1:1
	ds_read2_b32 v[132:133], v250 offset0:2 offset1:3
	ds_read2_b32 v[136:137], v250 offset0:4 offset1:5
	ds_read2_b32 v[140:141], v250 offset0:6 offset1:7
	ds_read2_b32 v[168:169], v250 offset0:8 offset1:9
	ds_read2_b32 v[172:173], v250 offset0:10 offset1:11
	ds_read2_b32 v[178:179], v250 offset0:12 offset1:13
	ds_read2_b32 v[182:183], v250 offset0:14 offset1:15
	ds_read2_b32 v[130:131], v250 offset0:32 offset1:33
	ds_read2_b32 v[134:135], v250 offset0:34 offset1:35
	ds_read2_b32 v[138:139], v250 offset0:36 offset1:37
	ds_read2_b32 v[142:143], v250 offset0:38 offset1:39
	ds_read2_b32 v[170:171], v250 offset0:40 offset1:41
	ds_read2_b32 v[174:175], v250 offset0:42 offset1:43
	ds_read2_b32 v[180:181], v250 offset0:44 offset1:45
	ds_read2_b32 v[184:185], v250 offset0:46 offset1:47
	s_waitcnt lgkmcnt(0)
	v_pk_add_f32 v[110:111], v[110:111], v[182:183]
	v_pk_add_f32 v[108:109], v[108:109], v[178:179]
	v_pk_add_f32 v[106:107], v[106:107], v[172:173]
	v_pk_add_f32 v[104:105], v[104:105], v[168:169]
	v_pk_add_f32 v[102:103], v[102:103], v[140:141]
	v_pk_add_f32 v[100:101], v[100:101], v[136:137]
	v_pk_add_f32 v[98:99], v[98:99], v[132:133]
	v_pk_add_f32 v[96:97], v[96:97], v[128:129]
	v_pk_add_f32 v[94:95], v[94:95], v[184:185]
	v_pk_add_f32 v[92:93], v[92:93], v[180:181]
	v_pk_add_f32 v[90:91], v[90:91], v[174:175]
	v_pk_add_f32 v[88:89], v[88:89], v[170:171]
	v_pk_add_f32 v[86:87], v[86:87], v[142:143]
	v_pk_add_f32 v[84:85], v[84:85], v[138:139]
	v_pk_add_f32 v[82:83], v[82:83], v[134:135]
	v_pk_add_f32 v[80:81], v[80:81], v[130:131]

.LBB0_645:
	s_waitcnt lgkmcnt(7)
	v_mfma_f32_32x32x16_bf16 v[48:63], v[128:131], v[170:173], v[48:63]
	v_add_f32_e32 v96, v97, v96
	v_add_f32_e32 v96, v98, v96
	v_add_f32_e32 v80, v81, v80
	v_add_f32_e32 v96, v99, v96
	s_waitcnt lgkmcnt(5)
	v_mfma_f32_32x32x16_bf16 v[0:15], v[136:139], v[170:173], v[0:15]
	s_add_i32 s4, s44, 0x9000
	s_cmp_lg_u32 s44, 0x12000
	s_cselect_b32 s44, s4, 0
	s_add_i32 s4, s45, 1
	v_add_f32_e32 v80, v82, v80
	v_add_f32_e32 v96, v100, v96
	v_add_f32_e32 v80, v83, v80
	v_add_f32_e32 v96, v101, v96
	v_mfma_f32_32x32x16_bf16 v[48:63], v[132:135], v[178:181], v[48:63]
	v_add_f32_e32 v80, v84, v80
	v_add_f32_e32 v96, v102, v96
	v_add_f32_e32 v80, v85, v80
	v_add_f32_e32 v96, v103, v96
	s_waitcnt lgkmcnt(4)
	v_mfma_f32_32x32x16_bf16 v[0:15], v[140:143], v[178:181], v[0:15]
	s_cmp_lg_u32 s45, 2
	s_cselect_b32 s45, s4, 0
	s_add_i32 s33, s33, 1
	s_add_u32 s10, s10, 0x60000
	s_addc_u32 s11, s11, 0
	v_add_f32_e32 v80, v86, v80
	v_add_f32_e32 v96, v104, v96
	v_add_f32_e32 v80, v87, v80
	v_add_f32_e32 v96, v105, v96
	v_add_f32_e32 v80, v88, v80
	v_add_f32_e32 v96, v106, v96
	v_add_f32_e32 v80, v89, v80
	v_add_f32_e32 v96, v107, v96
	s_add_i32 s20, s20, 64
	v_add_f32_e32 v80, v90, v80
	v_add_f32_e32 v96, v108, v96
	v_add_f32_e32 v80, v91, v80
	v_add_f32_e32 v96, v109, v96
	v_add_f32_e32 v80, v92, v80
	v_add_f32_e32 v96, v110, v96
	v_add_f32_e32 v80, v93, v80
	v_add_f32_e32 v96, v111, v96
	v_add_f32_e32 v80, v94, v80
	v_add_f32_e32 v96, v157, v96
	v_add_f32_e32 v80, v95, v80
	v_add_f32_e32 v157, v96, v80
	s_mov_b64 s[60:61], -1
	s_and_b64 vcc, exec, s[50:51]
	s_cbranch_vccz .LBB0_647
	s_waitcnt vmcnt(0) lgkmcnt(0)
	s_barrier
	s_mov_b64 s[60:61], 0

.Lv2p_flush:
	v_mfma_f32_32x32x16_bf16 v[32:47], v[182:185], v[170:173], v[32:47]
	v_mfma_f32_32x32x16_bf16 v[16:31], v[190:193], v[170:173], v[16:31]
	v_mfma_f32_32x32x16_bf16 v[32:47], v[186:189], v[178:181], v[32:47]
	v_mfma_f32_32x32x16_bf16 v[16:31], v[194:197], v[178:181], v[16:31]

.LBB0_683:
	v_add3_u32 v165, s57, v143, v163
	ds_read_b128 v[190:193], v165 offset:18432
	ds_read_b128 v[194:197], v165 offset:18448
	ds_read_b128 v[128:131], v165 offset:23040
	ds_read_b128 v[132:135], v165 offset:23056
	ds_read_b128 v[136:139], v165 offset:27648
	ds_read_b128 v[166:169], v165 offset:27664
	ds_read_b128 v[170:173], v165 offset:32256
	ds_read_b128 v[178:181], v165 offset:32272
	v_exp_f32_e32 v96, v96
	v_exp_f32_e32 v97, v97
	v_exp_f32_e32 v98, v98
	v_exp_f32_e32 v99, v99
	v_exp_f32_e32 v100, v100
	v_add_f32_e32 v198, v97, v96
	v_exp_f32_e32 v101, v101
	v_add_f32_e32 v198, v98, v198
	v_exp_f32_e32 v102, v102
	v_add_f32_e32 v198, v99, v198
	v_exp_f32_e32 v103, v103
	v_add_f32_e32 v198, v100, v198
	v_exp_f32_e32 v104, v104
	v_add_f32_e32 v198, v101, v198
	v_exp_f32_e32 v105, v105
	v_add_f32_e32 v198, v102, v198
	v_exp_f32_e32 v106, v106
	v_add_f32_e32 v198, v103, v198
	v_exp_f32_e32 v107, v107
	v_add_f32_e32 v198, v104, v198
	v_exp_f32_e32 v108, v108
	v_add_f32_e32 v198, v105, v198
	v_exp_f32_e32 v109, v109
	v_add_f32_e32 v198, v106, v198
	v_exp_f32_e32 v110, v110
	v_add_f32_e32 v198, v107, v198
	v_exp_f32_e32 v111, v111
	v_add_f32_e32 v198, v108, v198
	v_add_f32_e32 v198, v109, v198
	v_add_f32_e32 v198, v110, v198
	v_add_f32_e32 v198, v111, v198
	v_add_f32_e32 v157, v157, v198
	v_cvt_pk_bf16_f32 v96, v96, v97
	v_cvt_pk_bf16_f32 v97, v98, v99
	v_cvt_pk_bf16_f32 v98, v100, v101
	v_cvt_pk_bf16_f32 v99, v102, v103
	v_cvt_pk_bf16_f32 v100, v104, v105
	v_cvt_pk_bf16_f32 v101, v106, v107
	v_cvt_pk_bf16_f32 v102, v108, v109
	v_cvt_pk_bf16_f32 v103, v110, v111
	s_waitcnt lgkmcnt(7)
	v_mfma_f32_32x32x16_bf16 v[48:63], v[190:193], v[96:99], v[48:63]
	v_exp_f32_e32 v174, v80
	v_exp_f32_e32 v175, v81
	v_exp_f32_e32 v182, v82
	v_exp_f32_e32 v183, v83
	v_add_f32_e32 v80, v175, v174
	v_add_f32_e32 v80, v182, v80
	s_waitcnt lgkmcnt(5)
	v_mfma_f32_32x32x16_bf16 v[0:15], v[128:131], v[96:99], v[0:15]
	v_add_f32_e32 v80, v183, v80
	v_mfma_f32_32x32x16_bf16 v[48:63], v[194:197], v[100:103], v[48:63]
	v_exp_f32_e32 v128, v84
	v_exp_f32_e32 v129, v85
	v_exp_f32_e32 v130, v86
	v_exp_f32_e32 v131, v87
	v_add_f32_e32 v80, v128, v80
	v_add_f32_e32 v80, v129, v80
	v_add_f32_e32 v80, v130, v80
	s_waitcnt lgkmcnt(4)
	v_mfma_f32_32x32x16_bf16 v[0:15], v[132:135], v[100:103], v[0:15]
	v_add_f32_e32 v184, v131, v80
	ds_read_b128 v[80:83], v165 offset:18496
	ds_read_b128 v[84:87], v165 offset:18512
	ds_read_b128 v[104:107], v165 offset:23104
	ds_read_b128 v[108:111], v165 offset:23120
	s_waitcnt lgkmcnt(7)
	v_mfma_f32_32x32x16_bf16 v[32:47], v[136:139], v[96:99], v[32:47]
	v_exp_f32_e32 v132, v88
	v_exp_f32_e32 v133, v89
	v_exp_f32_e32 v134, v90
	v_exp_f32_e32 v135, v91
	v_add_f32_e32 v88, v132, v184
	v_add_f32_e32 v88, v133, v88
	v_add_f32_e32 v88, v134, v88
	s_waitcnt lgkmcnt(5)
	v_mfma_f32_32x32x16_bf16 v[16:31], v[170:173], v[96:99], v[16:31]
	v_add_f32_e32 v88, v135, v88
	v_exp_f32_e32 v96, v92
	v_mfma_f32_32x32x16_bf16 v[32:47], v[166:169], v[100:103], v[32:47]
	v_exp_f32_e32 v97, v93
	v_exp_f32_e32 v98, v94
	v_exp_f32_e32 v95, v95
	v_add_f32_e32 v88, v96, v88
	v_add_f32_e32 v88, v97, v88
	v_add_f32_e32 v88, v98, v88
	v_add_f32_e32 v88, v95, v88
	s_waitcnt lgkmcnt(4)
	v_mfma_f32_32x32x16_bf16 v[16:31], v[178:181], v[100:103], v[16:31]
	v_add_f32_e32 v157, v157, v88
	v_cvt_pk_bf16_f32 v88, v174, v175
	v_cvt_pk_bf16_f32 v89, v182, v183
	v_cvt_pk_bf16_f32 v90, v128, v129
	v_cvt_pk_bf16_f32 v91, v130, v131
	v_cvt_pk_bf16_f32 v92, v132, v133
	v_cvt_pk_bf16_f32 v93, v134, v135
	v_cvt_pk_bf16_f32 v94, v96, v97
	v_cvt_pk_bf16_f32 v95, v98, v95
	ds_read_b128 v[96:99], v165 offset:27712
	ds_read_b128 v[100:103], v165 offset:27728
	ds_read_b128 v[128:131], v165 offset:32320
	ds_read_b128 v[132:135], v165 offset:32336
	s_waitcnt lgkmcnt(7)
	v_mfma_f32_32x32x16_bf16 v[48:63], v[80:83], v[88:91], v[48:63]
	s_waitcnt lgkmcnt(5)
	v_mfma_f32_32x32x16_bf16 v[0:15], v[104:107], v[88:91], v[0:15]
	s_add_i32 s4, s9, 0x9000
	s_cmp_lg_u32 s9, 0x12000
	s_cselect_b32 s9, s4, 0
	s_add_i32 s4, s56, 1
	v_mfma_f32_32x32x16_bf16 v[48:63], v[84:87], v[92:95], v[48:63]
	s_waitcnt lgkmcnt(4)
	v_mfma_f32_32x32x16_bf16 v[0:15], v[108:111], v[92:95], v[0:15]
	s_cmp_lg_u32 s56, 2
	s_cselect_b32 s56, s4, 0
	s_add_i32 s8, s8, 1
	s_add_u32 s10, s10, 0x60000
	s_addc_u32 s11, s11, 0
	s_add_i32 s58, s58, 64
	s_cmpk_lg_i32 s58, 0x7c0
	s_waitcnt lgkmcnt(0)
	s_barrier
	s_cbranch_scc0 .Lv1s_flush
	s_add_i32 s57, s9, 0
	s_add_i32 s4, s57, s94
	v_add_u32_e32 v80, s4, v162
	v_add_u32_e32 v84, v80, v146
	ds_read_b128 v[80:83], v84
	ds_read_b128 v[220:223], v84 offset:32
	ds_read_b128 v[136:139], v84 offset:4608
	ds_read_b128 v[224:227], v84 offset:4640
	ds_read_b128 v[166:169], v84 offset:64
	ds_read_b128 v[170:173], v84 offset:96
	ds_read_b128 v[178:181], v84 offset:4672
	ds_read_b128 v[182:185], v84 offset:4704
	v_mfma_f32_32x32x16_bf16 v[32:47], v[96:99], v[88:91], v[32:47]
	v_mfma_f32_32x32x16_bf16 v[16:31], v[128:131], v[88:91], v[16:31]
	v_mfma_f32_32x32x16_bf16 v[32:47], v[100:103], v[92:95], v[32:47]
	v_mfma_f32_32x32x16_bf16 v[16:31], v[132:135], v[92:95], v[16:31]
	s_branch .Lv1s_body

.Lv1s_body:
	s_cmp_gt_u32 s8, 29
	s_cselect_b64 s[78:79], -1, 0
	s_and_b64 vcc, exec, s[78:79]
	s_cbranch_vccnz .LBB0_686
	s_mul_i32 vcc_lo, s56, 0x9000
	s_add_i32 vcc_hi, vcc_lo, s35
	s_and_b64 s[80:81], s[54:55], exec
	s_cselect_b32 m0, vcc_hi, s82
	s_nop 0
	global_load_lds_dwordx4 v[240:241], off
	s_add_i32 vcc_hi, vcc_lo, s33
	s_and_b64 s[80:81], s[64:65], exec
	s_cselect_b32 m0, vcc_hi, s2
	v_lshl_add_u64 v[240:241], v[240:241], 0, v[200:201]
	global_load_lds_dwordx4 v[242:243], off
	s_add_i32 vcc_hi, vcc_lo, s93
	s_and_b64 s[80:81], s[42:43], exec
	s_cselect_b32 m0, vcc_hi, s92
	v_lshl_add_u64 v[242:243], v[242:243], 0, v[202:203]
	global_load_lds_dwordx4 v[244:245], off
	s_add_i32 vcc_hi, vcc_lo, s45
	s_and_b64 s[80:81], s[24:25], exec
	s_cselect_b32 m0, vcc_hi, s97
	v_lshl_add_u64 v[244:245], v[244:245], 0, v[204:205]
	global_load_lds_dwordx4 v[246:247], off
	s_add_i32 vcc_hi, vcc_lo, s59
	s_and_b64 s[80:81], s[70:71], exec
	s_cselect_b32 m0, vcc_hi, s86
	v_lshl_add_u64 v[246:247], v[246:247], 0, v[206:207]
	global_load_lds_dwordx4 v[248:249], off
	v_lshl_add_u64 v[248:249], v[248:249], 0, v[208:209]

.Lattn_negm_keep_2:
	s_addk_i32 s16, 0xffa1
	s_cmp_lt_u32 s16, 0xfffffea3
	s_nop 0
	s_waitcnt lgkmcnt(7)
	v_mfma_f32_32x32x16_bf16 v[96:111], v[80:83], v[112:115], v[64:79]
	s_waitcnt lgkmcnt(5)
	v_mfma_f32_32x32x16_bf16 v[80:95], v[136:139], v[112:115], v[64:79]
	v_mfma_f32_32x32x16_bf16 v[96:111], v[220:223], v[116:119], v[96:111]
	s_waitcnt lgkmcnt(4)
	v_mfma_f32_32x32x16_bf16 v[80:95], v[224:227], v[116:119], v[80:95]
	s_waitcnt lgkmcnt(3)
	v_mfma_f32_32x32x16_bf16 v[96:111], v[166:169], v[120:123], v[96:111]
	s_waitcnt lgkmcnt(1)
	v_mfma_f32_32x32x16_bf16 v[80:95], v[178:181], v[120:123], v[80:95]
	v_mfma_f32_32x32x16_bf16 v[96:111], v[170:173], v[124:127], v[96:111]
	s_waitcnt lgkmcnt(0)
	v_mfma_f32_32x32x16_bf16 v[80:95], v[182:185], v[124:127], v[80:95]
	s_cbranch_scc1 .LBB0_688
	v_add_u32_e32 v180, s58, v164
	s_mov_b32 s80, 0x20380
	v_lshl_add_u32 v250, v180, 2, s80
	ds_read2_b32 v[128:129], v250 offset0:0 offset1:1
	ds_read2_b32 v[132:133], v250 offset0:2 offset1:3
	ds_read2_b32 v[136:137], v250 offset0:4 offset1:5
	ds_read2_b32 v[166:167], v250 offset0:6 offset1:7
	ds_read2_b32 v[170:171], v250 offset0:8 offset1:9
	ds_read2_b32 v[174:175], v250 offset0:10 offset1:11
	ds_read2_b32 v[180:181], v250 offset0:12 offset1:13
	ds_read2_b32 v[184:185], v250 offset0:14 offset1:15
	ds_read2_b32 v[130:131], v250 offset0:32 offset1:33
	ds_read2_b32 v[134:135], v250 offset0:34 offset1:35
	ds_read2_b32 v[138:139], v250 offset0:36 offset1:37
	ds_read2_b32 v[168:169], v250 offset0:38 offset1:39
	ds_read2_b32 v[172:173], v250 offset0:40 offset1:41
	ds_read2_b32 v[178:179], v250 offset0:42 offset1:43
	ds_read2_b32 v[182:183], v250 offset0:44 offset1:45
	ds_read2_b32 v[186:187], v250 offset0:46 offset1:47
	s_waitcnt lgkmcnt(0)
	v_pk_add_f32 v[110:111], v[110:111], v[184:185]
	v_pk_add_f32 v[108:109], v[108:109], v[180:181]
	v_pk_add_f32 v[106:107], v[106:107], v[174:175]
	v_pk_add_f32 v[104:105], v[104:105], v[170:171]
	v_pk_add_f32 v[102:103], v[102:103], v[166:167]
	v_pk_add_f32 v[100:101], v[100:101], v[136:137]
	v_pk_add_f32 v[98:99], v[98:99], v[132:133]
	v_pk_add_f32 v[96:97], v[96:97], v[128:129]
	v_pk_add_f32 v[94:95], v[94:95], v[186:187]
	v_pk_add_f32 v[92:93], v[92:93], v[182:183]
	v_pk_add_f32 v[90:91], v[90:91], v[178:179]
	v_pk_add_f32 v[88:89], v[88:89], v[172:173]
	v_pk_add_f32 v[86:87], v[86:87], v[168:169]
	v_pk_add_f32 v[84:85], v[84:85], v[138:139]
	v_pk_add_f32 v[82:83], v[82:83], v[134:135]
	v_pk_add_f32 v[80:81], v[80:81], v[130:131]

.LBB0_699:
	s_cmpk_eq_i32 s20, 0x7c0
	s_cbranch_scc1 .Lv2s_flush
	s_add_i32 s56, s44, 0
	v_add3_u32 v84, s56, v162, v146
	ds_read_b128 v[80:83], v84
	ds_read_b128 v[128:131], v84 offset:32
	ds_read_b128 v[132:135], v84 offset:4608
	ds_read_b128 v[136:139], v84 offset:4640
	ds_read_b128 v[140:143], v84 offset:64
	ds_read_b128 v[220:223], v84 offset:96
	ds_read_b128 v[224:227], v84 offset:4672
	ds_read_b128 v[228:231], v84 offset:4704
	v_mfma_f32_32x32x16_bf16 v[32:47], v[182:185], v[170:173], v[32:47]
	v_mfma_f32_32x32x16_bf16 v[16:31], v[190:193], v[170:173], v[16:31]
	v_mfma_f32_32x32x16_bf16 v[32:47], v[186:189], v[178:181], v[32:47]
	v_mfma_f32_32x32x16_bf16 v[16:31], v[194:197], v[178:181], v[16:31]
	s_branch .Lv2s_body
.LBB0_700:
	s_add_i32 s56, s44, 0
	v_add3_u32 v84, s56, v162, v146
	ds_read_b128 v[80:83], v84
	ds_read_b128 v[128:131], v84 offset:32
	ds_read_b128 v[132:135], v84 offset:4608
	ds_read_b128 v[136:139], v84 offset:4640
	ds_read_b128 v[140:143], v84 offset:64
	ds_read_b128 v[220:223], v84 offset:96
	ds_read_b128 v[224:227], v84 offset:4672
	ds_read_b128 v[228:231], v84 offset:4704
.Lv2s_body:
	s_add_i32 s16, s27, s20
	s_add_i32 s4, s16, 64
	s_cmpk_lt_i32 s4, 0xff42
	s_cselect_b32 s5, 1, 0
	s_cmpk_gt_i32 s4, 0x9e
	s_cselect_b32 s4, 2, s5
	s_cmp_eq_u32 s4, s32
	s_cbranch_scc1 .Lattn_negm_keep_3
	s_mov_b32 s32, s4
	s_cmp_eq_u32 s4, 1
	s_cselect_b64 vcc, -1, 0
	s_cmp_eq_u32 s4, 2
	s_cselect_b64 s[4:5], -1, 0
	v_cndmask_b32_e64 v84, 0, v160, s[4:5]
	v_cndmask_b32_e32 v252, v84, v159, vcc
	v_sub_f32_e32 v84, v252, v156
	v_mov_b32_e32 v79, v84
	v_mov_b32_e32 v78, v84
	v_mov_b32_e32 v77, v84
	v_mov_b32_e32 v76, v84
	v_mov_b32_e32 v75, v84
	v_mov_b32_e32 v74, v84
	v_mov_b32_e32 v73, v84
	v_mov_b32_e32 v72, v84
	v_mov_b32_e32 v71, v84
	v_mov_b32_e32 v70, v84
	v_mov_b32_e32 v69, v84
	v_mov_b32_e32 v68, v84
	v_mov_b32_e32 v67, v84
	v_mov_b32_e32 v66, v84
	v_mov_b32_e32 v65, v84
	v_mov_b32_e32 v64, v84
.Lattn_negm_keep_3:
	s_addk_i32 s16, 0xffa1
	s_cmp_lt_u32 s16, 0xfffffea3
	s_nop 0
	s_waitcnt lgkmcnt(7)
	v_mfma_f32_32x32x16_bf16 v[96:111], v[80:83], v[112:115], v[64:79]
	s_waitcnt lgkmcnt(5)
	v_mfma_f32_32x32x16_bf16 v[80:95], v[132:135], v[112:115], v[64:79]
	v_mfma_f32_32x32x16_bf16 v[96:111], v[128:131], v[116:119], v[96:111]
	s_waitcnt lgkmcnt(4)
	v_mfma_f32_32x32x16_bf16 v[80:95], v[136:139], v[116:119], v[80:95]
	s_waitcnt lgkmcnt(3)
	v_mfma_f32_32x32x16_bf16 v[96:111], v[140:143], v[120:123], v[96:111]
	s_waitcnt lgkmcnt(1)
	v_mfma_f32_32x32x16_bf16 v[80:95], v[224:227], v[120:123], v[80:95]
	v_mfma_f32_32x32x16_bf16 v[96:111], v[220:223], v[124:127], v[96:111]
	s_waitcnt lgkmcnt(0)
	v_mfma_f32_32x32x16_bf16 v[80:95], v[228:231], v[124:127], v[80:95]
	s_cbranch_scc1 .LBB0_702
	v_add_u32_e32 v178, s20, v166
	s_mov_b32 s57, 0x20380
	v_lshl_add_u32 v250, v178, 2, s57
	ds_read2_b32 v[128:129], v250 offset0:0 offset1:1
	ds_read2_b32 v[132:133], v250 offset0:2 offset1:3
	ds_read2_b32 v[136:137], v250 offset0:4 offset1:5
	ds_read2_b32 v[140:141], v250 offset0:6 offset1:7
	ds_read2_b32 v[168:169], v250 offset0:8 offset1:9
	ds_read2_b32 v[172:173], v250 offset0:10 offset1:11
	ds_read2_b32 v[178:179], v250 offset0:12 offset1:13
	ds_read2_b32 v[182:183], v250 offset0:14 offset1:15
	ds_read2_b32 v[130:131], v250 offset0:32 offset1:33
	ds_read2_b32 v[134:135], v250 offset0:34 offset1:35
	ds_read2_b32 v[138:139], v250 offset0:36 offset1:37
	ds_read2_b32 v[142:143], v250 offset0:38 offset1:39
	ds_read2_b32 v[170:171], v250 offset0:40 offset1:41
	ds_read2_b32 v[174:175], v250 offset0:42 offset1:43
	ds_read2_b32 v[180:181], v250 offset0:44 offset1:45
	ds_read2_b32 v[184:185], v250 offset0:46 offset1:47
	s_waitcnt lgkmcnt(0)
	v_pk_add_f32 v[110:111], v[110:111], v[182:183]
	v_pk_add_f32 v[108:109], v[108:109], v[178:179]
	v_pk_add_f32 v[106:107], v[106:107], v[172:173]
	v_pk_add_f32 v[104:105], v[104:105], v[168:169]
	v_pk_add_f32 v[102:103], v[102:103], v[140:141]
	v_pk_add_f32 v[100:101], v[100:101], v[136:137]
	v_pk_add_f32 v[98:99], v[98:99], v[132:133]
	v_pk_add_f32 v[96:97], v[96:97], v[128:129]
	v_pk_add_f32 v[94:95], v[94:95], v[184:185]
	v_pk_add_f32 v[92:93], v[92:93], v[180:181]
	v_pk_add_f32 v[90:91], v[90:91], v[174:175]
	v_pk_add_f32 v[88:89], v[88:89], v[170:171]
	v_pk_add_f32 v[86:87], v[86:87], v[142:143]
	v_pk_add_f32 v[84:85], v[84:85], v[138:139]
	v_pk_add_f32 v[82:83], v[82:83], v[134:135]
	v_pk_add_f32 v[80:81], v[80:81], v[130:131]

.LBB0_706:
	s_waitcnt lgkmcnt(7)
	v_mfma_f32_32x32x16_bf16 v[48:63], v[128:131], v[170:173], v[48:63]
	v_add_f32_e32 v96, v97, v96
	v_add_f32_e32 v96, v98, v96
	v_add_f32_e32 v80, v81, v80
	v_add_f32_e32 v96, v99, v96
	s_waitcnt lgkmcnt(5)
	v_mfma_f32_32x32x16_bf16 v[0:15], v[136:139], v[170:173], v[0:15]
	s_add_i32 s4, s44, 0x9000
	s_cmp_lg_u32 s44, 0x12000
	s_cselect_b32 s44, s4, 0
	v_add_f32_e32 v80, v82, v80
	v_add_f32_e32 v96, v100, v96
	v_add_f32_e32 v80, v83, v80
	v_add_f32_e32 v96, v101, v96
	v_mfma_f32_32x32x16_bf16 v[48:63], v[132:135], v[178:181], v[48:63]
	v_add_f32_e32 v80, v84, v80
	v_add_f32_e32 v96, v102, v96
	v_add_f32_e32 v80, v85, v80
	v_add_f32_e32 v96, v103, v96
	s_waitcnt lgkmcnt(4)
	v_mfma_f32_32x32x16_bf16 v[0:15], v[140:143], v[178:181], v[0:15]
	s_add_i32 s4, s45, 1
	s_cmp_lg_u32 s45, 2
	s_cselect_b32 s45, s4, 0
	v_add_f32_e32 v80, v86, v80
	v_add_f32_e32 v96, v104, v96
	v_add_f32_e32 v80, v87, v80
	v_add_f32_e32 v96, v105, v96
	v_add_f32_e32 v80, v88, v80
	v_add_f32_e32 v96, v106, v96
	v_add_f32_e32 v80, v89, v80
	v_add_f32_e32 v96, v107, v96
	s_add_i32 s33, s33, 1
	s_add_i32 s20, s20, 64
	v_add_f32_e32 v80, v90, v80
	v_add_f32_e32 v96, v108, v96
	v_add_f32_e32 v80, v91, v80
	v_add_f32_e32 v96, v109, v96
	v_add_f32_e32 v80, v92, v80
	v_add_f32_e32 v96, v110, v96
	v_add_f32_e32 v80, v93, v80
	v_add_f32_e32 v96, v111, v96
	v_add_f32_e32 v80, v94, v80
	v_add_f32_e32 v96, v157, v96
	v_add_f32_e32 v80, v95, v80
	v_add_f32_e32 v157, v96, v80
	s_mov_b64 s[62:63], -1
	s_and_b64 vcc, exec, s[60:61]
	s_cbranch_vccz .LBB0_708
	s_waitcnt vmcnt(0) lgkmcnt(0)
	s_barrier
	s_mov_b64 s[62:63], 0
